# v52 + per-tile K/V LDS-DMA loads issued behind the step-1 LDS read burst instead of right after the tile barrier
# baseline (speedup 1.0000x reference)
; #define SBAR() __builtin_amdgcn_sched_barrier(0)
; #define ATT_DMA_K(t) do { const bf16_t* kg_ = Kh + (size_t)(t) * 64 * LDK; LAS unsigned char* sb_ = lds + ((t) & 3) * KBUF; \
;     _Pragma("unroll") for (int i_ = 0; i_ < NKP; ++i_) __builtin_amdgcn_global_load_lds((const unsigned*)(kg_ + kgo[i_]), (LAS unsigned*)(sb_ + (wid + 8 * i_) * 1024), 16, 0, 0); } while (0)
; #define ATT_DMA_V(t, vs) do { const bf16_t* vg_ = Vh + (size_t)(t) * 64 * LDV; LAS unsigned char* sb_ = lds + V_OFF + (vs) * SHM_V; \
;     _Pragma("unroll") for (int i_ = 0; i_ < 2; ++i_) __builtin_amdgcn_global_load_lds((const unsigned*)(vg_ + vgo[i_]), (LAS unsigned*)(sb_ + (2 * wid + i_) * 1024), 16, 0, 0); } while (0)
; #define ATT_SEG(t) do { if constexpr (MODE != 0) { if (((t) == tL && tL > 0) || (t) == tR) { const float f_ = (t) == tR ? fR : fL; l_reg *= f_; \
;     _Pragma("unroll") for (int d = 0; d < 4; ++d) _Pragma("unroll") for (int r = 0; r < 16; ++r) o[d][r] *= f_; } } } while (0)
; #define ATT_TOP(N) do { asm volatile("s_waitcnt vmcnt(%0)" :: "n"(N) : "memory"); __builtin_amdgcn_s_barrier(); asm volatile("" ::: "memory"); } while (0)
; template <int DQK, int MODE, int LDQ, int LDK, int LDV> ...
;     ...
;     for (int j = 0; j < NT; ++j) {
;         if (j + 2 < NT) ATT_TOP(NKP + 2); else ATT_TOP(0);
;         if (j + 3 < NT) ATT_DMA_K(j + 3);
;         if (j + 2 < NT) ATT_DMA_V(j + 2, v2);
;         ATT_SEG(j); SBAR();
.Lstg_d0_pre_9:
.LBB0_1920:
	s_and_b32 s1, s22, 0x6000
	s_add_i32 s98, s59, s1
	s_lshl_b32 s1, s96, 14
	s_cmp_lt_u32 s33, 0x100
	s_cbranch_scc0 .Lstg_d0_top_10
	s_waitcnt vmcnt(3)
	s_barrier
.Lstg_d0_top_10:
	s_setprio 0
	s_add_i32 s99, s95, s1
	s_add_i32 s100, s99, 0x400
	s_add_i32 s1, s62, s0
	s_add_i32 s74, s6, s0
	s_cmp_eq_u32 s1, 1
	s_cselect_b64 s[2:3], -1, 0
	s_and_b64 vcc, s[4:5], s[2:3]
	s_cmp_eq_u32 s74, 1
	s_cselect_b64 s[2:3], -1, 0
	s_or_b64 vcc, s[2:3], vcc
	s_andn2_b64 vcc, exec, vcc
	s_mov_b32 s1, s23
	s_cbranch_vccnz .LBB0_1922
	v_cndmask_b32_e64 v122, v112, v113, s[2:3]
	v_pk_mul_f32 v[14:15], v[14:15], v[122:123] op_sel_hi:[1,0]
	v_pk_mul_f32 v[12:13], v[12:13], v[122:123] op_sel_hi:[1,0]
	v_pk_mul_f32 v[10:11], v[10:11], v[122:123] op_sel_hi:[1,0]
	v_pk_mul_f32 v[8:9], v[8:9], v[122:123] op_sel_hi:[1,0]
	v_pk_mul_f32 v[6:7], v[6:7], v[122:123] op_sel_hi:[1,0]
	v_pk_mul_f32 v[4:5], v[4:5], v[122:123] op_sel_hi:[1,0]
	v_pk_mul_f32 v[2:3], v[2:3], v[122:123] op_sel_hi:[1,0]
	v_pk_mul_f32 v[0:1], v[0:1], v[122:123] op_sel_hi:[1,0]
	v_pk_mul_f32 v[62:63], v[62:63], v[122:123] op_sel_hi:[1,0]
	v_pk_mul_f32 v[60:61], v[60:61], v[122:123] op_sel_hi:[1,0]
	v_pk_mul_f32 v[58:59], v[58:59], v[122:123] op_sel_hi:[1,0]
	v_pk_mul_f32 v[56:57], v[56:57], v[122:123] op_sel_hi:[1,0]
	v_pk_mul_f32 v[54:55], v[54:55], v[122:123] op_sel_hi:[1,0]
	v_pk_mul_f32 v[52:53], v[52:53], v[122:123] op_sel_hi:[1,0]
	v_pk_mul_f32 v[50:51], v[50:51], v[122:123] op_sel_hi:[1,0]
	v_pk_mul_f32 v[48:49], v[48:49], v[122:123] op_sel_hi:[1,0]
	v_pk_mul_f32 v[46:47], v[46:47], v[122:123] op_sel_hi:[1,0]
	v_pk_mul_f32 v[44:45], v[44:45], v[122:123] op_sel_hi:[1,0]
	v_pk_mul_f32 v[42:43], v[42:43], v[122:123] op_sel_hi:[1,0]
	v_pk_mul_f32 v[40:41], v[40:41], v[122:123] op_sel_hi:[1,0]
	v_pk_mul_f32 v[38:39], v[38:39], v[122:123] op_sel_hi:[1,0]
	v_pk_mul_f32 v[36:37], v[36:37], v[122:123] op_sel_hi:[1,0]
	v_pk_mul_f32 v[34:35], v[34:35], v[122:123] op_sel_hi:[1,0]
	v_pk_mul_f32 v[32:33], v[32:33], v[122:123] op_sel_hi:[1,0]
	v_pk_mul_f32 v[30:31], v[30:31], v[122:123] op_sel_hi:[1,0]
	v_pk_mul_f32 v[28:29], v[28:29], v[122:123] op_sel_hi:[1,0]
	v_pk_mul_f32 v[26:27], v[26:27], v[122:123] op_sel_hi:[1,0]
	v_pk_mul_f32 v[24:25], v[24:25], v[122:123] op_sel_hi:[1,0]
	v_pk_mul_f32 v[22:23], v[22:23], v[122:123] op_sel_hi:[1,0]
	v_pk_mul_f32 v[20:21], v[20:21], v[122:123] op_sel_hi:[1,0]
	v_pk_mul_f32 v[18:19], v[18:19], v[122:123] op_sel_hi:[1,0]
	v_pk_mul_f32 v[16:17], v[16:17], v[122:123] op_sel_hi:[1,0]
	v_mul_f32_e32 v120, v120, v122
; DI int v_rd_base(int lane) { return ((lane & 3) << 3) | (((lane >> 2) & 3) << 6) | (((lane >> 4) & 1) << 5) | (((lane >> 5) & 1) << 8); }
; template <int DQK, int MODE, int LDQ, int LDK, int LDV> ...
;     ...
;     const int vbase = (int)(unsigned)(size_t)lds + V_OFF + v_rd_base(lane);
;     ...
;     constexpr int NDA = ND0 > 6 ? 6 : ND0;
.LBB0_1922:
	s_add_i32 s3, s0, -1
	s_add_i32 s2, s22, 0xffffa000
	s_and_b32 s2, s2, 0x6000
	v_add_u32_e32 v121, s2, v114
	v_add_u32_e32 v122, v121, v115
	v_add_u32_e32 v126, v121, v116
	ds_read_b128 v[122:125], v122 offset:4096
	ds_read_b128 v[132:135], v126 offset:4096
	v_add_u32_e32 v126, v121, v117
	v_add_u32_e32 v121, v121, v118
	s_lshl_b32 s2, s1, 14
	ds_read_b128 v[136:139], v126 offset:4096
	ds_read_b128 v[140:143], v121 offset:4096
	v_add_u32_e32 v121, s2, v106
	ds_read_b64_tr_b16 v[144:145], v121 offset:0
	ds_read_b64_tr_b16 v[146:147], v121 offset:0x800
	ds_read_b64_tr_b16 v[148:149], v121 offset:0x1000
	ds_read_b64_tr_b16 v[150:151], v121 offset:0x1800
	ds_read_b64_tr_b16 v[152:153], v121 offset:0x200
	ds_read_b64_tr_b16 v[154:155], v121 offset:0xa00
	ds_read_b64_tr_b16 v[156:157], v121 offset:0x1200
	ds_read_b64_tr_b16 v[158:159], v121 offset:0x1a00
	ds_read_b64_tr_b16 v[162:163], v121 offset:0x400
	ds_read_b64_tr_b16 v[164:165], v121 offset:0xc00
	ds_read_b64_tr_b16 v[166:167], v121 offset:0x1400
	ds_read_b64_tr_b16 v[168:169], v121 offset:0x1c00
	ds_read_b64_tr_b16 v[170:171], v121 offset:0x600
	ds_read_b64_tr_b16 v[172:173], v121 offset:0xe00
	ds_read_b64_tr_b16 v[174:175], v121 offset:0x1600
	ds_read_b64_tr_b16 v[176:177], v121 offset:0x1e00
	s_mov_b32 m0, s98
	s_nop 0
	global_load_lds_dwordx4 v[100:101], off
	s_mov_b32 m0, s99
	s_nop 0
	global_load_lds_dwordx4 v[102:103], off
	s_mov_b32 m0, s100
	s_nop 0
	global_load_lds_dwordx4 v[104:105], off
	s_setprio 2
	v_exp_f32_e32 v64, v64
	v_exp_f32_e32 v65, v65
	v_exp_f32_e32 v66, v66
	v_exp_f32_e32 v67, v67
	v_exp_f32_e32 v68, v68
	v_exp_f32_e32 v69, v69
	v_add_f32_e32 v126, v65, v64
	v_exp_f32_e32 v70, v70
	v_add_f32_e32 v126, v66, v126
	v_exp_f32_e32 v71, v71
	v_add_f32_e32 v126, v67, v126
	v_exp_f32_e32 v72, v72
	v_add_f32_e32 v126, v68, v126
	v_exp_f32_e32 v73, v73
	v_add_f32_e32 v126, v69, v126
	v_exp_f32_e32 v74, v74
	v_add_f32_e32 v126, v70, v126
	v_exp_f32_e32 v75, v75
	v_add_f32_e32 v126, v71, v126
	v_exp_f32_e32 v76, v76
	v_add_f32_e32 v126, v72, v126
	v_exp_f32_e32 v77, v77
	v_add_f32_e32 v126, v73, v126
	v_exp_f32_e32 v78, v78
	v_add_f32_e32 v126, v74, v126
	v_exp_f32_e32 v79, v79
	v_add_f32_e32 v126, v75, v126
	v_add_f32_e32 v126, v76, v126
	v_add_f32_e32 v126, v77, v126
	v_add_f32_e32 v126, v78, v126
	v_add_f32_e32 v126, v79, v126
	v_add_f32_e32 v120, v126, v120
	v_cvt_pk_bf16_f32 v64, v64, v65
	v_cvt_pk_bf16_f32 v65, v66, v67
	v_cvt_pk_bf16_f32 v66, v68, v69
	v_cvt_pk_bf16_f32 v67, v70, v71
	v_cvt_pk_bf16_f32 v68, v72, v73
	v_cvt_pk_bf16_f32 v69, v74, v75
	v_cvt_pk_bf16_f32 v70, v76, v77
	v_cvt_pk_bf16_f32 v71, v78, v79
	s_nop 0
	v_permlane32_swap_b32_e32 v64, v66
	v_permlane32_swap_b32_e32 v65, v67
	v_permlane32_swap_b32_e32 v68, v70
	v_permlane32_swap_b32_e32 v69, v71
	s_waitcnt lgkmcnt(0)
	s_setprio 1
	v_mfma_f32_32x32x16_bf16 v[0:15], v[64:67], v[144:147], v[0:15]
	s_cmp_lt_i32 s3, s55
	s_cselect_b64 vcc, -1, 0
	s_cmp_ge_i32 s3, s97
	s_cselect_b64 s[74:75], -1, 0
	s_or_b64 s[74:75], vcc, s[74:75]
	s_and_b64 vcc, exec, s[74:75]
	v_mfma_f32_32x32x16_bf16 v[48:63], v[64:67], v[152:155], v[48:63]
	v_mfma_f32_32x32x16_bf16 v[32:47], v[64:67], v[162:165], v[32:47]
	v_mfma_f32_32x32x16_bf16 v[16:31], v[64:67], v[170:173], v[16:31]
	v_mfma_f32_32x32x16_bf16 v[0:15], v[68:71], v[148:151], v[0:15]
	v_mfma_f32_32x32x16_bf16 v[48:63], v[68:71], v[156:159], v[48:63]
	v_mfma_f32_32x32x16_bf16 v[32:47], v[68:71], v[166:169], v[32:47]
	v_mfma_f32_32x32x16_bf16 v[16:31], v[68:71], v[174:177], v[16:31]
	v_mfma_f32_32x32x16_bf16 v[64:79], v[122:125], v[92:95], 0
	v_mfma_f32_32x32x16_bf16 v[64:79], v[132:135], v[88:91], v[64:79]
	v_mfma_f32_32x32x16_bf16 v[64:79], v[136:139], v[84:87], v[64:79]
	v_mfma_f32_32x32x16_bf16 v[64:79], v[140:143], v[80:83], v[64:79]
	s_setprio 0
	v_add_u32_e32 v122, s7, v119
	s_cbranch_vccnz .LBB0_1924
	v_add_u32_e32 v138, 0x28908, v122
	v_add_u32_e32 v140, 0x28920, v122
	v_add_u32_e32 v142, 0x28928, v122
	v_add_u32_e32 v124, 0x28940, v122
	v_add_u32_e32 v126, 0x28948, v122
	v_add_u32_e32 v132, 0x28960, v122
	v_add_u32_e32 v134, 0x28968, v122
	v_add_u32_e32 v123, 0x28900, v122
	ds_read2_b32 v[124:125], v124 offset1:1
	ds_read2_b32 v[126:127], v126 offset1:1
	ds_read2_b32 v[132:133], v132 offset1:1
	ds_read2_b32 v[134:135], v134 offset1:1
	ds_read2_b32 v[136:137], v123 offset1:1
	ds_read2_b32 v[138:139], v138 offset1:1
	ds_read2_b32 v[140:141], v140 offset1:1
	ds_read2_b32 v[142:143], v142 offset1:1
	s_waitcnt lgkmcnt(0)
	v_pk_add_f32 v[78:79], v[78:79], v[134:135]
	v_pk_add_f32 v[76:77], v[76:77], v[132:133]
	v_pk_add_f32 v[74:75], v[74:75], v[126:127]
	v_pk_add_f32 v[72:73], v[72:73], v[124:125]
	v_pk_add_f32 v[70:71], v[70:71], v[142:143]
	v_pk_add_f32 v[68:69], v[68:69], v[140:141]
	v_pk_add_f32 v[66:67], v[66:67], v[138:139]
	v_pk_add_f32 v[64:65], v[64:65], v[136:137]

; #define SBAR() __builtin_amdgcn_sched_barrier(0)
; #define ATT_DMA_K(t) do { const bf16_t* kg_ = Kh + (size_t)(t) * 64 * LDK; LAS unsigned char* sb_ = lds + ((t) & 3) * KBUF; \
;     _Pragma("unroll") for (int i_ = 0; i_ < NKP; ++i_) __builtin_amdgcn_global_load_lds((const unsigned*)(kg_ + kgo[i_]), (LAS unsigned*)(sb_ + (wid + 8 * i_) * 1024), 16, 0, 0); } while (0)
; #define ATT_DMA_V(t, vs) do { const bf16_t* vg_ = Vh + (size_t)(t) * 64 * LDV; LAS unsigned char* sb_ = lds + V_OFF + (vs) * SHM_V; \
;     _Pragma("unroll") for (int i_ = 0; i_ < 2; ++i_) __builtin_amdgcn_global_load_lds((const unsigned*)(vg_ + vgo[i_]), (LAS unsigned*)(sb_ + (2 * wid + i_) * 1024), 16, 0, 0); } while (0)
; #define ATT_SEG(t) do { if constexpr (MODE != 0) { if (((t) == tL && tL > 0) || (t) == tR) { const float f_ = (t) == tR ? fR : fL; l_reg *= f_; \
;     _Pragma("unroll") for (int d = 0; d < 4; ++d) _Pragma("unroll") for (int r = 0; r < 16; ++r) o[d][r] *= f_; } } } while (0)
; #define ATT_TOP(N) do { asm volatile("s_waitcnt vmcnt(%0)" :: "n"(N) : "memory"); __builtin_amdgcn_s_barrier(); asm volatile("" ::: "memory"); } while (0)
; template <int DQK, int MODE, int LDQ, int LDK, int LDV> ...
;     ...
;     for (int j = 0; j < NT; ++j) {
;         if (j + 2 < NT) ATT_TOP(NKP + 2); else ATT_TOP(0);
;         if (j + 3 < NT) ATT_DMA_K(j + 3);
;         if (j + 2 < NT) ATT_DMA_V(j + 2, v2);
;         ATT_SEG(j); SBAR();
.Lstg_d1_pre_17:
.LBB0_1951:
	s_and_b32 s2, s22, 0x6000
	s_add_i32 s98, s94, s2
	s_lshl_b32 s2, s1, 14
	s_cmp_lt_u32 s33, 0x100
	s_cbranch_scc0 .Lstg_d1_top_18
	s_waitcnt vmcnt(3)
	s_barrier
.Lstg_d1_top_18:
	s_setprio 0
	s_add_i32 s99, s48, s2
	s_add_i32 s100, s99, 0x400
	s_add_i32 s2, s53, s0
	s_add_i32 s23, s6, s0
	s_cmp_eq_u32 s2, 1
	s_cselect_b64 s[2:3], -1, 0
	s_and_b64 s[74:75], s[4:5], s[2:3]
	s_cmp_eq_u32 s23, 1
	s_cselect_b64 s[2:3], -1, 0
	s_or_b64 s[74:75], s[2:3], s[74:75]
	s_andn2_b64 vcc, exec, s[74:75]
	s_mov_b32 s23, s62
	s_cbranch_vccnz .LBB0_1953
	v_cndmask_b32_e64 v122, v112, v113, s[2:3]
	v_pk_mul_f32 v[14:15], v[14:15], v[122:123] op_sel_hi:[1,0]
	v_pk_mul_f32 v[12:13], v[12:13], v[122:123] op_sel_hi:[1,0]
	v_pk_mul_f32 v[10:11], v[10:11], v[122:123] op_sel_hi:[1,0]
	v_pk_mul_f32 v[8:9], v[8:9], v[122:123] op_sel_hi:[1,0]
	v_pk_mul_f32 v[6:7], v[6:7], v[122:123] op_sel_hi:[1,0]
	v_pk_mul_f32 v[4:5], v[4:5], v[122:123] op_sel_hi:[1,0]
	v_pk_mul_f32 v[2:3], v[2:3], v[122:123] op_sel_hi:[1,0]
	v_pk_mul_f32 v[0:1], v[0:1], v[122:123] op_sel_hi:[1,0]
	v_pk_mul_f32 v[62:63], v[62:63], v[122:123] op_sel_hi:[1,0]
	v_pk_mul_f32 v[60:61], v[60:61], v[122:123] op_sel_hi:[1,0]
	v_pk_mul_f32 v[58:59], v[58:59], v[122:123] op_sel_hi:[1,0]
	v_pk_mul_f32 v[56:57], v[56:57], v[122:123] op_sel_hi:[1,0]
	v_pk_mul_f32 v[54:55], v[54:55], v[122:123] op_sel_hi:[1,0]
	v_pk_mul_f32 v[52:53], v[52:53], v[122:123] op_sel_hi:[1,0]
	v_pk_mul_f32 v[50:51], v[50:51], v[122:123] op_sel_hi:[1,0]
	v_pk_mul_f32 v[48:49], v[48:49], v[122:123] op_sel_hi:[1,0]
	v_pk_mul_f32 v[30:31], v[30:31], v[122:123] op_sel_hi:[1,0]
	v_pk_mul_f32 v[28:29], v[28:29], v[122:123] op_sel_hi:[1,0]
	v_pk_mul_f32 v[26:27], v[26:27], v[122:123] op_sel_hi:[1,0]
	v_pk_mul_f32 v[24:25], v[24:25], v[122:123] op_sel_hi:[1,0]
	v_pk_mul_f32 v[22:23], v[22:23], v[122:123] op_sel_hi:[1,0]
	v_pk_mul_f32 v[20:21], v[20:21], v[122:123] op_sel_hi:[1,0]
	v_pk_mul_f32 v[18:19], v[18:19], v[122:123] op_sel_hi:[1,0]
	v_pk_mul_f32 v[16:17], v[16:17], v[122:123] op_sel_hi:[1,0]
	v_pk_mul_f32 v[46:47], v[46:47], v[122:123] op_sel_hi:[1,0]
	v_pk_mul_f32 v[44:45], v[44:45], v[122:123] op_sel_hi:[1,0]
	v_pk_mul_f32 v[42:43], v[42:43], v[122:123] op_sel_hi:[1,0]
	v_pk_mul_f32 v[40:41], v[40:41], v[122:123] op_sel_hi:[1,0]
	v_pk_mul_f32 v[38:39], v[38:39], v[122:123] op_sel_hi:[1,0]
	v_pk_mul_f32 v[36:37], v[36:37], v[122:123] op_sel_hi:[1,0]
	v_pk_mul_f32 v[34:35], v[34:35], v[122:123] op_sel_hi:[1,0]
	v_pk_mul_f32 v[32:33], v[32:33], v[122:123] op_sel_hi:[1,0]
	v_mul_f32_e32 v120, v120, v122
; DI int v_rd_base(int lane) { return ((lane & 3) << 3) | (((lane >> 2) & 3) << 6) | (((lane >> 4) & 1) << 5) | (((lane >> 5) & 1) << 8); }
; template <int DQK, int MODE, int LDQ, int LDK, int LDV> ...
;     ...
;     const int vbase = (int)(unsigned)(size_t)lds + V_OFF + v_rd_base(lane);
;     ...
;     constexpr int NDA = ND0 > 6 ? 6 : ND0;
.LBB0_1953:
	s_add_i32 s3, s0, -1
	s_add_i32 s2, s22, 0xffffa000
	s_and_b32 s2, s2, 0x6000
	v_add_u32_e32 v121, s2, v114
	v_add_u32_e32 v122, v121, v115
	v_add_u32_e32 v126, v121, v116
	ds_read_b128 v[122:125], v122 offset:4096
	ds_read_b128 v[132:135], v126 offset:4096
	v_add_u32_e32 v126, v121, v117
	v_add_u32_e32 v121, v121, v118
	s_lshl_b32 s2, s23, 14
	ds_read_b128 v[136:139], v126 offset:4096
	ds_read_b128 v[140:143], v121 offset:4096
	v_add_u32_e32 v121, s2, v106
	ds_read_b64_tr_b16 v[144:145], v121 offset:0
	ds_read_b64_tr_b16 v[146:147], v121 offset:0x800
	ds_read_b64_tr_b16 v[148:149], v121 offset:0x1000
	ds_read_b64_tr_b16 v[150:151], v121 offset:0x1800
	ds_read_b64_tr_b16 v[152:153], v121 offset:0x200
	ds_read_b64_tr_b16 v[154:155], v121 offset:0xa00
	ds_read_b64_tr_b16 v[156:157], v121 offset:0x1200
	ds_read_b64_tr_b16 v[158:159], v121 offset:0x1a00
	ds_read_b64_tr_b16 v[162:163], v121 offset:0x400
	ds_read_b64_tr_b16 v[164:165], v121 offset:0xc00
	ds_read_b64_tr_b16 v[166:167], v121 offset:0x1400
	ds_read_b64_tr_b16 v[168:169], v121 offset:0x1c00
	ds_read_b64_tr_b16 v[170:171], v121 offset:0x600
	ds_read_b64_tr_b16 v[172:173], v121 offset:0xe00
	ds_read_b64_tr_b16 v[174:175], v121 offset:0x1600
	ds_read_b64_tr_b16 v[176:177], v121 offset:0x1e00
	s_mov_b32 m0, s98
	s_nop 0
	global_load_lds_dwordx4 v[100:101], off
	s_mov_b32 m0, s99
	s_nop 0
	global_load_lds_dwordx4 v[102:103], off
	s_mov_b32 m0, s100
	s_nop 0
	global_load_lds_dwordx4 v[104:105], off
	s_setprio 2
	v_exp_f32_e32 v64, v64
	v_exp_f32_e32 v65, v65
	v_exp_f32_e32 v66, v66
	v_exp_f32_e32 v67, v67
	v_exp_f32_e32 v68, v68
	v_exp_f32_e32 v69, v69
	v_add_f32_e32 v126, v65, v64
	v_exp_f32_e32 v70, v70
	v_add_f32_e32 v126, v66, v126
	v_exp_f32_e32 v71, v71
	v_add_f32_e32 v126, v67, v126
	v_exp_f32_e32 v72, v72
	v_add_f32_e32 v126, v68, v126
	v_exp_f32_e32 v73, v73
	v_add_f32_e32 v126, v69, v126
	v_exp_f32_e32 v74, v74
	v_add_f32_e32 v126, v70, v126
	v_exp_f32_e32 v75, v75
	v_add_f32_e32 v126, v71, v126
	v_exp_f32_e32 v76, v76
	v_add_f32_e32 v126, v72, v126
	v_exp_f32_e32 v77, v77
	v_add_f32_e32 v126, v73, v126
	v_exp_f32_e32 v78, v78
	v_add_f32_e32 v126, v74, v126
	v_exp_f32_e32 v79, v79
	v_add_f32_e32 v126, v75, v126
	v_add_f32_e32 v126, v76, v126
	v_add_f32_e32 v126, v77, v126
	v_add_f32_e32 v126, v78, v126
	v_add_f32_e32 v126, v79, v126
	v_add_f32_e32 v120, v126, v120
	v_cvt_pk_bf16_f32 v64, v64, v65
	v_cvt_pk_bf16_f32 v65, v66, v67
	v_cvt_pk_bf16_f32 v66, v68, v69
	v_cvt_pk_bf16_f32 v67, v70, v71
	v_cvt_pk_bf16_f32 v68, v72, v73
	v_cvt_pk_bf16_f32 v69, v74, v75
	v_cvt_pk_bf16_f32 v70, v76, v77
	v_cvt_pk_bf16_f32 v71, v78, v79
	s_nop 0
	v_permlane32_swap_b32_e32 v64, v66
	v_permlane32_swap_b32_e32 v65, v67
	v_permlane32_swap_b32_e32 v68, v70
	v_permlane32_swap_b32_e32 v69, v71
	s_waitcnt lgkmcnt(0)
	s_setprio 1
	v_mfma_f32_32x32x16_bf16 v[0:15], v[64:67], v[144:147], v[0:15]
	s_cmp_lt_i32 s3, s47
	s_cselect_b64 s[74:75], -1, 0
	s_cmp_ge_i32 s3, s52
	s_cselect_b64 s[90:91], -1, 0
	s_or_b64 s[74:75], s[74:75], s[90:91]
	s_and_b64 vcc, exec, s[74:75]
	v_mfma_f32_32x32x16_bf16 v[48:63], v[64:67], v[152:155], v[48:63]
	v_mfma_f32_32x32x16_bf16 v[16:31], v[64:67], v[162:165], v[16:31]
	v_mfma_f32_32x32x16_bf16 v[32:47], v[64:67], v[170:173], v[32:47]
	v_mfma_f32_32x32x16_bf16 v[0:15], v[68:71], v[148:151], v[0:15]
	v_mfma_f32_32x32x16_bf16 v[48:63], v[68:71], v[156:159], v[48:63]
	v_mfma_f32_32x32x16_bf16 v[16:31], v[68:71], v[166:169], v[16:31]
	v_mfma_f32_32x32x16_bf16 v[32:47], v[68:71], v[174:177], v[32:47]
	v_mfma_f32_32x32x16_bf16 v[64:79], v[122:125], v[92:95], 0
	v_mfma_f32_32x32x16_bf16 v[64:79], v[132:135], v[88:91], v[64:79]
	v_mfma_f32_32x32x16_bf16 v[64:79], v[136:139], v[84:87], v[64:79]
	v_mfma_f32_32x32x16_bf16 v[64:79], v[140:143], v[80:83], v[64:79]
	s_setprio 0
	v_add_u32_e32 v122, s7, v119
	s_cbranch_vccnz .LBB0_1955
	v_add_u32_e32 v138, 0x28908, v122
	v_add_u32_e32 v140, 0x28920, v122
	v_add_u32_e32 v142, 0x28928, v122
	v_add_u32_e32 v124, 0x28940, v122
	v_add_u32_e32 v126, 0x28948, v122
	v_add_u32_e32 v132, 0x28960, v122
	v_add_u32_e32 v134, 0x28968, v122
	v_add_u32_e32 v123, 0x28900, v122
	ds_read2_b32 v[124:125], v124 offset1:1
	ds_read2_b32 v[126:127], v126 offset1:1
	ds_read2_b32 v[132:133], v132 offset1:1
	ds_read2_b32 v[134:135], v134 offset1:1
	ds_read2_b32 v[136:137], v123 offset1:1
	ds_read2_b32 v[138:139], v138 offset1:1
	ds_read2_b32 v[140:141], v140 offset1:1
	ds_read2_b32 v[142:143], v142 offset1:1
	s_waitcnt lgkmcnt(0)
	v_pk_add_f32 v[78:79], v[78:79], v[134:135]
	v_pk_add_f32 v[76:77], v[76:77], v[132:133]
	v_pk_add_f32 v[74:75], v[74:75], v[126:127]
	v_pk_add_f32 v[72:73], v[72:73], v[124:125]
	v_pk_add_f32 v[70:71], v[70:71], v[142:143]
	v_pk_add_f32 v[68:69], v[68:69], v[140:141]
	v_pk_add_f32 v[66:67], v[66:67], v[138:139]
	v_pk_add_f32 v[64:65], v[64:65], v[136:137]

; #define SBAR() __builtin_amdgcn_sched_barrier(0)
; #define ATT_DMA_K(t) do { const bf16_t* kg_ = Kh + (size_t)(t) * 64 * LDK; LAS unsigned char* sb_ = lds + ((t) & 3) * KBUF; \
;     _Pragma("unroll") for (int i_ = 0; i_ < NKP; ++i_) __builtin_amdgcn_global_load_lds((const unsigned*)(kg_ + kgo[i_]), (LAS unsigned*)(sb_ + (wid + 8 * i_) * 1024), 16, 0, 0); } while (0)
; #define ATT_DMA_V(t, vs) do { const bf16_t* vg_ = Vh + (size_t)(t) * 64 * LDV; LAS unsigned char* sb_ = lds + V_OFF + (vs) * SHM_V; \
;     _Pragma("unroll") for (int i_ = 0; i_ < 2; ++i_) __builtin_amdgcn_global_load_lds((const unsigned*)(vg_ + vgo[i_]), (LAS unsigned*)(sb_ + (2 * wid + i_) * 1024), 16, 0, 0); } while (0)
; #define ATT_SEG(t) do { if constexpr (MODE != 0) { if (((t) == tL && tL > 0) || (t) == tR) { const float f_ = (t) == tR ? fR : fL; l_reg *= f_; \
;     _Pragma("unroll") for (int d = 0; d < 4; ++d) _Pragma("unroll") for (int r = 0; r < 16; ++r) o[d][r] *= f_; } } } while (0)
; #define ATT_TOP(N) do { asm volatile("s_waitcnt vmcnt(%0)" :: "n"(N) : "memory"); __builtin_amdgcn_s_barrier(); asm volatile("" ::: "memory"); } while (0)
; template <int DQK, int MODE, int LDQ, int LDK, int LDV> ...
;     ...
;     for (int j = 0; j < NT; ++j) {
;         if (j + 2 < NT) ATT_TOP(NKP + 2); else ATT_TOP(0);
;         if (j + 3 < NT) ATT_DMA_K(j + 3);
;         if (j + 2 < NT) ATT_DMA_V(j + 2, v2);
;         ATT_SEG(j); SBAR();
;         ATT_STEP(pA, pB, 0, v0, true, 1, j);
.Lstg_mla_pre_1:
.LBB0_1982:
	s_and_b32 s1, s43, 3
	s_mulk_i32 s1, 0x6000
	s_add_i32 s98, s49, s1
	s_cmp_lt_u32 s33, 0x100
	s_cbranch_scc0 .Lstg_mla_top_2
	s_waitcnt vmcnt(5)
	s_barrier
.Lstg_mla_top_2:
	s_setprio 0
	s_mov_b32 s0, s5
	s_mov_b32 s5, s44
	s_mov_b32 s44, s4
	s_lshl_b32 s99, s4, 14
	s_add_i32 s99, s52, s99
	s_add_i32 s1, s43, -3
	s_and_b32 s1, s1, 3
	s_mulk_i32 s1, 0x6000
	v_add_u32_e32 v246, s1, v158
	v_add_u32_e32 v174, v246, v151
	v_add_u32_e32 v178, v246, v149
	v_add_u32_e32 v182, v246, v148
	v_add_u32_e32 v186, v246, v147
	s_lshl_b32 s1, s0, 14
	ds_read_b128 v[190:193], v174 offset:12416
	ds_read_b128 v[194:197], v178 offset:12416
	ds_read_b128 v[174:177], v174 offset:12288
	ds_read_b128 v[178:181], v178 offset:12288
	ds_read_b128 v[182:185], v182 offset:12288
	ds_read_b128 v[186:189], v186 offset:12288
	v_add_u32_e32 v254, s1, v130
	ds_read_b64_tr_b16 v[198:199], v254 offset:0
	ds_read_b64_tr_b16 v[200:201], v254 offset:0x800
	ds_read_b64_tr_b16 v[202:203], v254 offset:0x1000
	ds_read_b64_tr_b16 v[204:205], v254 offset:0x1800
	ds_read_b64_tr_b16 v[206:207], v254 offset:0x200
	ds_read_b64_tr_b16 v[208:209], v254 offset:0xa00
	ds_read_b64_tr_b16 v[210:211], v254 offset:0x1200
	ds_read_b64_tr_b16 v[212:213], v254 offset:0x1a00
	ds_read_b64_tr_b16 v[214:215], v254 offset:0x400
	ds_read_b64_tr_b16 v[216:217], v254 offset:0xc00
	ds_read_b64_tr_b16 v[218:219], v254 offset:0x1400
	ds_read_b64_tr_b16 v[220:221], v254 offset:0x1c00
	ds_read_b64_tr_b16 v[222:223], v254 offset:0x600
	ds_read_b64_tr_b16 v[224:225], v254 offset:0xe00
	ds_read_b64_tr_b16 v[226:227], v254 offset:0x1600
	ds_read_b64_tr_b16 v[228:229], v254 offset:0x1e00
	s_mov_b32 m0, s98
	s_nop 0
	global_load_lds_dwordx4 v136, s[34:35]
	s_add_i32 m0, s98, 0x2000
	s_nop 0
	global_load_lds_dwordx4 v138, s[34:35]
	s_add_i32 m0, s98, 0x4000
	s_nop 0
	global_load_lds_dwordx4 v140, s[34:35]
	s_mov_b32 m0, s99
	s_nop 0
	global_load_lds_dwordx4 v144, s[34:35]
	s_add_i32 m0, s99, 0x400
	s_nop 0
	global_load_lds_dwordx4 v142, s[34:35]
	s_setprio 2
	v_exp_f32_e32 v64, v64
	v_exp_f32_e32 v65, v65
	v_exp_f32_e32 v66, v66
	v_exp_f32_e32 v67, v67
	v_exp_f32_e32 v68, v68
	v_exp_f32_e32 v69, v69
	v_add_f32_e32 v230, v65, v64
	v_exp_f32_e32 v70, v70
	v_add_f32_e32 v230, v66, v230
	v_exp_f32_e32 v71, v71
	v_add_f32_e32 v230, v67, v230
	v_exp_f32_e32 v72, v72
	v_add_f32_e32 v230, v68, v230
	v_exp_f32_e32 v73, v73
	v_add_f32_e32 v230, v69, v230
	v_exp_f32_e32 v74, v74
	v_add_f32_e32 v230, v70, v230
	v_exp_f32_e32 v75, v75
	v_add_f32_e32 v230, v71, v230
	v_exp_f32_e32 v76, v76
	v_add_f32_e32 v230, v72, v230
	v_exp_f32_e32 v77, v77
	v_add_f32_e32 v230, v73, v230
	v_exp_f32_e32 v78, v78
	v_add_f32_e32 v230, v74, v230
	v_exp_f32_e32 v79, v79
	v_add_f32_e32 v230, v75, v230
	v_add_f32_e32 v230, v76, v230
	v_add_f32_e32 v230, v77, v230
	v_add_f32_e32 v230, v78, v230
	v_add_f32_e32 v230, v79, v230
	v_add_f32_e32 v173, v173, v230
	v_cvt_pk_bf16_f32 v64, v64, v65
	v_cvt_pk_bf16_f32 v65, v66, v67
	v_cvt_pk_bf16_f32 v66, v68, v69
	v_cvt_pk_bf16_f32 v67, v70, v71
	v_cvt_pk_bf16_f32 v68, v72, v73
	v_cvt_pk_bf16_f32 v69, v74, v75
	v_cvt_pk_bf16_f32 v70, v76, v77
	v_cvt_pk_bf16_f32 v71, v78, v79
	s_nop 0
	v_permlane32_swap_b32_e32 v64, v66
	v_permlane32_swap_b32_e32 v65, v67
	v_permlane32_swap_b32_e32 v68, v70
	v_permlane32_swap_b32_e32 v69, v71
	s_waitcnt lgkmcnt(0)
	v_add_u32_e32 v72, v246, v151
	v_add_u32_e32 v73, v246, v149
	v_add_u32_e32 v74, v246, v148
	v_add_u32_e32 v75, v246, v147
	ds_read_b128 v[230:233], v74 offset:12416
	ds_read_b128 v[234:237], v75 offset:12416
	ds_read_b128 v[238:241], v72 offset:12544
	ds_read_b128 v[242:245], v73 offset:12544
	ds_read_b128 v[246:249], v74 offset:12544
	ds_read_b128 v[250:253], v75 offset:12544
	s_setprio 1
	v_mfma_f32_32x32x16_bf16 v[48:63], v[64:67], v[198:201], v[48:63]
	v_mfma_f32_32x32x16_bf16 v[32:47], v[64:67], v[206:209], v[32:47]
	v_mfma_f32_32x32x16_bf16 v[16:31], v[64:67], v[214:217], v[16:31]
	v_mfma_f32_32x32x16_bf16 v[0:15], v[64:67], v[222:225], v[0:15]
	v_mfma_f32_32x32x16_bf16 v[48:63], v[68:71], v[202:205], v[48:63]
	v_mfma_f32_32x32x16_bf16 v[32:47], v[68:71], v[210:213], v[32:47]
	v_mfma_f32_32x32x16_bf16 v[16:31], v[68:71], v[218:221], v[16:31]
	v_mfma_f32_32x32x16_bf16 v[0:15], v[68:71], v[226:229], v[0:15]
	s_waitcnt lgkmcnt(0)
; #define SBAR() __builtin_amdgcn_sched_barrier(0)
; #define ATT_DMA_K(t) do { const bf16_t* kg_ = Kh + (size_t)(t) * 64 * LDK; LAS unsigned char* sb_ = lds + ((t) & 3) * KBUF; \
;     _Pragma("unroll") for (int i_ = 0; i_ < NKP; ++i_) __builtin_amdgcn_global_load_lds((const unsigned*)(kg_ + kgo[i_]), (LAS unsigned*)(sb_ + (wid + 8 * i_) * 1024), 16, 0, 0); } while (0)
; #define ATT_DMA_V(t, vs) do { const bf16_t* vg_ = Vh + (size_t)(t) * 64 * LDV; LAS unsigned char* sb_ = lds + V_OFF + (vs) * SHM_V; \
;     _Pragma("unroll") for (int i_ = 0; i_ < 2; ++i_) __builtin_amdgcn_global_load_lds((const unsigned*)(vg_ + vgo[i_]), (LAS unsigned*)(sb_ + (2 * wid + i_) * 1024), 16, 0, 0); } while (0)
; #define ATT_SEG(t) do { if constexpr (MODE != 0) { if (((t) == tL && tL > 0) || (t) == tR) { const float f_ = (t) == tR ? fR : fL; l_reg *= f_; \
;     _Pragma("unroll") for (int d = 0; d < 4; ++d) _Pragma("unroll") for (int r = 0; r < 16; ++r) o[d][r] *= f_; } } } while (0)
; #define ATT_TOP(N) do { asm volatile("s_waitcnt vmcnt(%0)" :: "n"(N) : "memory"); __builtin_amdgcn_s_barrier(); asm volatile("" ::: "memory"); } while (0)
; template <int DQK, int MODE, int LDQ, int LDK, int LDV> ...
;     ...
;     for (int j = 0; j < NT; ++j) {
;         if (j + 2 < NT) ATT_TOP(NKP + 2); else ATT_TOP(0);
;         if (j + 3 < NT) ATT_DMA_K(j + 3);
;         if (j + 2 < NT) ATT_DMA_V(j + 2, v2);
;         ATT_SEG(j); SBAR();
;         ATT_STEP(pA, pB, 0, v0, true, 1, j);
;         ATT_STEP(pB, pA, 1, v0, (j + 1 < NT), 0, j + 1);
	v_mfma_f32_32x32x16_bf16 v[64:79], v[174:177], v[80:83], 0
	v_mfma_f32_32x32x16_bf16 v[64:79], v[178:181], v[84:87], v[64:79]
	v_mfma_f32_32x32x16_bf16 v[64:79], v[182:185], v[88:91], v[64:79]
	v_mfma_f32_32x32x16_bf16 v[64:79], v[186:189], v[92:95], v[64:79]
	v_mfma_f32_32x32x16_bf16 v[64:79], v[190:193], v[96:99], v[64:79]
	v_mfma_f32_32x32x16_bf16 v[64:79], v[194:197], v[100:103], v[64:79]
	v_mfma_f32_32x32x16_bf16 v[64:79], v[230:233], v[104:107], v[64:79]
	v_mfma_f32_32x32x16_bf16 v[64:79], v[234:237], v[108:111], v[64:79]
	v_mfma_f32_32x32x16_bf16 v[64:79], v[238:241], v[112:115], v[64:79]
	v_mfma_f32_32x32x16_bf16 v[64:79], v[242:245], v[116:119], v[64:79]
	v_mfma_f32_32x32x16_bf16 v[64:79], v[246:249], v[120:123], v[64:79]
	v_mfma_f32_32x32x16_bf16 v[64:79], v[250:253], v[124:127], v[64:79]
	s_setprio 0
	s_add_i32 s4, s43, -2
	s_and_b32 s4, s4, 3
	s_mulk_i32 s4, 0x6000
	v_add_u32_e32 v246, s4, v158
	v_add_u32_e32 v174, v246, v151
	v_add_u32_e32 v178, v246, v149
	v_add_u32_e32 v182, v246, v148
	v_add_u32_e32 v186, v246, v147
	ds_read_b128 v[190:193], v174 offset:128
	ds_read_b128 v[194:197], v178 offset:128
	ds_read_b128 v[174:177], v174
	ds_read_b128 v[178:181], v178
	ds_read_b128 v[182:185], v182
	ds_read_b128 v[186:189], v186
	ds_read_b64_tr_b16 v[198:199], v254 offset:0x2000
	ds_read_b64_tr_b16 v[200:201], v254 offset:0x2800
	ds_read_b64_tr_b16 v[202:203], v254 offset:0x3000
	ds_read_b64_tr_b16 v[204:205], v254 offset:0x3800
	ds_read_b64_tr_b16 v[206:207], v254 offset:0x2200
	ds_read_b64_tr_b16 v[208:209], v254 offset:0x2a00
	ds_read_b64_tr_b16 v[210:211], v254 offset:0x3200
	ds_read_b64_tr_b16 v[212:213], v254 offset:0x3a00
	ds_read_b64_tr_b16 v[214:215], v254 offset:0x2400
	ds_read_b64_tr_b16 v[216:217], v254 offset:0x2c00
	ds_read_b64_tr_b16 v[218:219], v254 offset:0x3400
	ds_read_b64_tr_b16 v[220:221], v254 offset:0x3c00
	ds_read_b64_tr_b16 v[222:223], v254 offset:0x2600
	ds_read_b64_tr_b16 v[224:225], v254 offset:0x2e00
	ds_read_b64_tr_b16 v[226:227], v254 offset:0x3600
	ds_read_b64_tr_b16 v[228:229], v254 offset:0x3e00
	s_setprio 2
	v_exp_f32_e32 v64, v64
	v_exp_f32_e32 v65, v65
	v_exp_f32_e32 v66, v66
	v_exp_f32_e32 v67, v67
	v_exp_f32_e32 v68, v68
	v_exp_f32_e32 v69, v69
	v_add_f32_e32 v230, v65, v64
	v_exp_f32_e32 v70, v70
	v_add_f32_e32 v230, v66, v230
	v_exp_f32_e32 v71, v71
	v_add_f32_e32 v230, v67, v230
	v_exp_f32_e32 v72, v72
	v_add_f32_e32 v230, v68, v230
	v_exp_f32_e32 v73, v73
	v_add_f32_e32 v230, v69, v230
	v_exp_f32_e32 v74, v74
	v_add_f32_e32 v230, v70, v230
	v_exp_f32_e32 v75, v75
	v_add_f32_e32 v230, v71, v230
	v_exp_f32_e32 v76, v76
	v_add_f32_e32 v230, v72, v230
	v_exp_f32_e32 v77, v77
	v_add_f32_e32 v230, v73, v230
	v_exp_f32_e32 v78, v78
	v_add_f32_e32 v230, v74, v230
	v_exp_f32_e32 v79, v79
	v_add_f32_e32 v230, v75, v230
	v_add_f32_e32 v230, v76, v230
	v_add_f32_e32 v230, v77, v230
	v_add_f32_e32 v230, v78, v230
	v_add_f32_e32 v230, v79, v230
	v_add_f32_e32 v173, v173, v230
	v_cvt_pk_bf16_f32 v64, v64, v65
	v_cvt_pk_bf16_f32 v65, v66, v67
	v_cvt_pk_bf16_f32 v66, v68, v69
	v_cvt_pk_bf16_f32 v67, v70, v71
	v_cvt_pk_bf16_f32 v68, v72, v73
	v_cvt_pk_bf16_f32 v69, v74, v75
	v_cvt_pk_bf16_f32 v70, v76, v77
	v_cvt_pk_bf16_f32 v71, v78, v79
	s_nop 0
	v_permlane32_swap_b32_e32 v64, v66
	v_permlane32_swap_b32_e32 v65, v67
	v_permlane32_swap_b32_e32 v68, v70
	v_permlane32_swap_b32_e32 v69, v71
	s_waitcnt lgkmcnt(0)
	v_add_u32_e32 v72, v246, v151
	v_add_u32_e32 v73, v246, v149
	v_add_u32_e32 v74, v246, v148
	v_add_u32_e32 v75, v246, v147
	ds_read_b128 v[230:233], v74 offset:128
	ds_read_b128 v[234:237], v75 offset:128
	ds_read_b128 v[238:241], v72 offset:256
	ds_read_b128 v[242:245], v73 offset:256
	ds_read_b128 v[246:249], v74 offset:256
	ds_read_b128 v[250:253], v75 offset:256
	s_setprio 1
	s_cmp_lt_u32 s33, 0x100
	s_cbranch_scc1 .Lstg_mla_mid_3
	s_waitcnt vmcnt(5)
	s_barrier
